# v83 + one more deferred weight copy per idle S-team workgroup in the Y-GEMM slot (cap 6 to 7), 32 fewer leftover copies in P6
# speedup vs baseline: 1.0063x; 1.0063x over previous
.LBB0_734:
	s_or_b64 exec, exec, s[6:7]
	s_andn2_b64 vcc, exec, s[4:5]
	s_waitcnt lgkmcnt(0)
	s_barrier
	s_cbranch_vccnz .LBB0_775
	s_mov_b64 s[4:5], s[0:1]
	s_load_dwordx2 s[16:17], s[4:5], 0xe0
	s_mov_b32 s28, 7
	v_mov_b32_e32 v3, 0
	s_movk_i32 s30, 0x400
	s_movk_i32 s31, 0x204
	s_waitcnt lgkmcnt(0)
	s_add_u32 s4, s16, 0xa000
	s_addc_u32 s5, s17, 0
	s_add_u32 s6, s16, 0x1800000
	s_addc_u32 s7, s17, 0
	s_add_u32 s8, s16, 0xd00000
	s_addc_u32 s9, s17, 0
	s_add_u32 s10, s16, 0xb00000
	s_addc_u32 s11, s17, 0
	s_add_u32 s12, s16, 0x900000
	s_addc_u32 s13, s17, 0
	s_add_u32 s14, s16, 0x800000
	s_addc_u32 s15, s17, 0
	s_add_u32 s16, s16, 0x200000
	s_addc_u32 s17, s17, 0
	s_add_i32 s29, 0, 0x20180
	v_mov_b32_e32 v1, s29
	s_movk_i32 s34, 0x3ff
	s_movk_i32 s35, 0x700
	s_movk_i32 s37, 0xb00
	s_mov_b32 s44, 0x5040100
	s_mov_b32 s45, 0x7060302
	v_mov_b32_e32 v14, 0x80
	s_branch .LBB0_738
